# FFN weights of layer L+1 converted at the end of layer L's FFN-up step by the workgroups that own one tile less; phase 0 converts layer 0's only
# speedup vs baseline: 1.0039x; 1.0039x over previous
.LBB0_59:
	s_or_b64 exec, exec, s[0:1]
	s_mov_b32 s3, s24
	s_load_dwordx2 s[38:39], s[60:61], 0x8
	s_load_dwordx2 s[40:41], s[60:61], 0x10
	s_load_dwordx2 s[42:43], s[60:61], 0x30
	s_load_dwordx2 s[44:45], s[60:61], 0x38
	s_load_dwordx2 s[48:49], s[60:61], 0x40
	s_load_dwordx2 s[50:51], s[60:61], 0x78
	s_load_dwordx2 s[52:53], s[60:61], 0x80
	s_load_dwordx2 s[54:55], s[60:61], 0x88
	s_load_dwordx2 s[56:57], s[60:61], 0xa0
	v_lshrrev_b32_e32 v8, 6, v175
	v_and_b32_e32 v9, 63, v175
	v_lshrrev_b32_e32 v1, 3, v9
	v_and_b32_e32 v2, 7, v9
	v_readfirstlane_b32 s20, v8
	v_lshlrev_b32_e32 v5, 5, v1
	v_lshlrev_b32_e32 v10, 14, v8
	v_mul_u32_u24_e32 v11, 33, v1
	v_lshl_add_u32 v11, v2, 2, v11
	v_lshl_add_u32 v3, v11, 2, v10
	v_mul_u32_u24_e32 v11, 264, v1
	v_add_u32_e32 v11, v11, v2
	v_lshl_add_u32 v4, v11, 2, v10
	v_mov_b32_e32 v16, 0
	v_mov_b32_e32 v17, 0
	v_mov_b32_e32 v18, 0
	v_mov_b32_e32 v19, 0
	v_lshl_add_u32 v12, s3, 9, v175
	v_lshlrev_b32_e32 v13, 4, v12
	s_movk_i32 s21, 0x6000
	v_cmp_gt_u32_e32 vcc, s21, v12
	s_and_saveexec_b64 s[22:23], vcc
	s_add_u32 s0, s36, 0x1820000
	s_addc_u32 s1, s37, 0
	global_store_dwordx4 v13, v[16:19], s[0:1]
	s_add_u32 s0, s0, 0x1080000
	s_addc_u32 s1, s1, 0
	global_store_dwordx4 v13, v[16:19], s[0:1]
	s_mov_b64 exec, s[22:23]
	s_lshl_b32 s2, s3, 3
	s_add_u32 s2, s2, s20
	s_waitcnt lgkmcnt(0)
	s_cmp_lt_u32 s2, 15040
	s_cselect_b32 s10, 1, 0
	s_cselect_b32 s20, s2, 0
	s_cmp_lt_u32 s20, 10816
	s_cbranch_scc0 .Lp0_ffn_1
	s_cmp_lt_u32 s20, 5408
	s_cselect_b32 s21, 0, 1
	s_cselect_b32 s22, 0, 5408
	s_sub_u32 s20, s20, s22
	s_cmp_lt_u32 s20, 768
	s_cbranch_scc1 .Lp0_k0_3
	s_sub_u32 s20, s20, 768
	s_cmp_lt_u32 s20, 512
	s_cbranch_scc1 .Lp0_k1_4
	s_sub_u32 s20, s20, 512
	s_cmp_lt_u32 s20, 3104
	s_cbranch_scc1 .Lp0_k2_5
	s_sub_u32 s20, s20, 3104
	s_branch .Lp0_k3_6
.Lp0_ffn_1:
	s_sub_u32 s20, s20, 10816
	s_mov_b32 s21, 0
	s_cmp_lt_u32 s20, 4224
	s_cselect_b32 s22, 0, 4224
	s_cselect_b32 s23, 0, 1
	s_sub_u32 s20, s20, s22
	s_add_u32 s21, s21, s23
	s_cmp_lt_u32 s20, 4224
	s_cselect_b32 s22, 0, 4224
	s_cselect_b32 s23, 0, 1
	s_sub_u32 s20, s20, s22
	s_add_u32 s21, s21, s23
	s_cmp_lt_u32 s20, 4224
	s_cselect_b32 s22, 0, 4224
	s_cselect_b32 s23, 0, 1
	s_sub_u32 s20, s20, s22
	s_add_u32 s21, s21, s23
	s_cmp_lt_u32 s20, 2816
	s_cbranch_scc1 .Lp0_k4_7
	s_sub_u32 s20, s20, 2816
	s_branch .Lp0_k5_8
.Lp0_k0_3:
	s_mul_hi_u32 s22, s20, 0x5555556
	s_mul_i32 s23, s22, 48
	s_sub_u32 s23, s20, s23
	s_lshl_b32 s22, s22, 6
	s_lshl_b32 s23, s23, 5
	s_mul_i32 s24, s21, 0x600000
	s_mul_i32 s25, s22, 6144
	s_add_u32 s24, s24, s25
	s_lshl_b32 s25, s23, 2
	s_add_u32 s24, s24, s25
	s_add_u32 s26, s40, s24
	s_addc_u32 s27, s41, 0
	s_mov_b32 s29, 0x1800
	s_lshl_b32 s24, s21, 12
	s_lshl_b32 s25, s22, 2
	s_add_u32 s24, s24, s25
	s_add_u32 s8, s38, s24
	s_addc_u32 s9, s39, 0
	s_mov_b32 s7, 1
	s_mov_b32 s30, s23
	s_mul_i32 s30, s30, 2048
	s_mul_i32 s24, s21, 0x500000
	s_add_u32 s30, s30, s24
	s_lshl_b32 s24, s22, 1
	s_add_u32 s30, s30, s24
	s_add_u32 s30, s30, 0x200000
	s_add_u32 s4, s36, s30
	s_addc_u32 s5, s37, 0
	s_mov_b32 s6, 0x800
	s_branch .Lp0_go_9
.Lp0_k1_4:
	s_lshr_b32 s22, s20, 5
	s_and_b32 s23, s20, 31
	s_lshl_b32 s22, s22, 6
	s_lshl_b32 s23, s23, 5
	s_mul_i32 s24, s21, 0x400000
	s_mul_i32 s25, s22, 4096
	s_add_u32 s24, s24, s25
	s_lshl_b32 s25, s23, 2
	s_add_u32 s24, s24, s25
	s_add_u32 s26, s42, s24
	s_addc_u32 s27, s43, 0
	s_mov_b32 s29, 0x1000
	s_mov_b32 s8, s26
	s_mov_b32 s9, s27
	s_mov_b32 s7, 0
	s_mov_b32 s30, s23
	s_mul_i32 s30, s30, 2048
	s_mul_i32 s24, s21, 0x500000
	s_add_u32 s30, s30, s24
	s_lshl_b32 s24, s22, 1
	s_add_u32 s30, s30, s24
	s_add_u32 s30, s30, 0x500000
	s_add_u32 s4, s36, s30
	s_addc_u32 s5, s37, 0
	s_mov_b32 s6, 0x800
	s_branch .Lp0_go_9
.Lp0_k2_5:
	s_mul_hi_u32 s22, s20, 0x151d07f
	s_mul_i32 s23, s22, 194
	s_sub_u32 s23, s20, s23
	s_lshl_b32 s22, s22, 6
	s_lshl_b32 s23, s23, 5
	s_mul_i32 s24, s21, 0x1840000
	s_mul_i32 s25, s22, 24832
	s_add_u32 s24, s24, s25
	s_lshl_b32 s25, s23, 2
	s_add_u32 s24, s24, s25
	s_add_u32 s26, s48, s24
	s_addc_u32 s27, s49, 0
	s_mov_b32 s29, 0x6100
	s_lshl_b32 s24, s21, 12
	s_lshl_b32 s25, s22, 2
	s_add_u32 s24, s24, s25
	s_add_u32 s8, s44, s24
	s_addc_u32 s9, s45, 0
	s_mov_b32 s7, 1
	s_mov_b32 s30, s23
	s_mul_i32 s30, s30, 2048
	s_mul_i32 s24, s21, 0x1080000
	s_add_u32 s30, s30, s24
	s_lshl_b32 s24, s22, 1
	s_add_u32 s30, s30, s24
	s_add_u32 s30, s30, 0xc00000
	s_add_u32 s4, s36, s30
	s_addc_u32 s5, s37, 0
	s_mov_b32 s6, 0x800
	s_branch .Lp0_go_9
.Lp0_k3_6:
	s_lshr_b32 s22, s20, 5
	s_and_b32 s23, s20, 31
	s_lshl_b32 s22, s22, 6
	s_lshl_b32 s23, s23, 5
	s_mul_i32 s24, s21, 0x800000
	s_mul_i32 s25, s22, 4096
	s_add_u32 s24, s24, s25
	s_lshl_b32 s25, s23, 2
	s_add_u32 s24, s24, s25
	s_add_u32 s26, s50, s24
	s_addc_u32 s27, s51, 0
	s_mov_b32 s29, 0x1000
	s_mov_b32 s8, s26
	s_mov_b32 s9, s27
	s_mov_b32 s7, 0
	s_mov_b32 s30, s23
	s_mul_i32 s30, s30, 4096
	s_mul_i32 s24, s21, 0x1080000
	s_add_u32 s30, s30, s24
	s_lshl_b32 s24, s22, 1
	s_add_u32 s30, s30, s24
	s_add_u32 s30, s30, 0x1880000
	s_add_u32 s4, s36, s30
	s_addc_u32 s5, s37, 0
	s_mov_b32 s6, 0x1000
	s_branch .Lp0_go_9
.Lp0_k4_7:
	s_mul_hi_u32 s22, s20, 0x1745d18
	s_mul_i32 s23, s22, 176
	s_sub_u32 s23, s20, s23
	s_lshl_b32 s22, s22, 6
	s_lshl_b32 s23, s23, 5
	s_mul_i32 s24, s21, 0x1600000
	s_mul_i32 s25, s22, 22528
	s_add_u32 s24, s24, s25
	s_lshl_b32 s25, s23, 2
	s_add_u32 s24, s24, s25
	s_add_u32 s26, s54, s24
	s_addc_u32 s27, s55, 0
	s_mov_b32 s29, 0x5800
	s_lshl_b32 s24, s21, 12
	s_lshl_b32 s25, s22, 2
	s_add_u32 s24, s24, s25
	s_add_u32 s8, s52, s24
	s_addc_u32 s9, s53, 0
	s_mov_b32 s7, 1
	s_cmp_lt_u32 s23, 2816
	s_cselect_b32 s24, 0, 2816
	s_cselect_b32 s25, 0, 128
	s_sub_u32 s24, s23, s24
	s_lshr_b32 s30, s24, 7
	s_lshl_b32 s30, s30, 8
	s_and_b32 s24, s24, 127
	s_add_u32 s30, s30, s24
	s_add_u32 s30, s30, s25
	s_mul_i32 s30, s30, 2048
	s_mul_i32 s24, s21, 0x1080000
	s_add_u32 s30, s30, s24
	s_lshl_b32 s24, s22, 1
	s_add_u32 s30, s30, s24
	s_add_u32 s30, s30, 0x2d00000
	s_add_u32 s4, s36, s30
	s_addc_u32 s5, s37, 0
	s_mov_b32 s6, 0x800
	s_branch .Lp0_go_9
.Lp0_k5_8:
	s_lshr_b32 s22, s20, 5
	s_and_b32 s23, s20, 31
	s_lshl_b32 s22, s22, 6
	s_lshl_b32 s23, s23, 5
	s_mul_i32 s24, s21, 0xb00000
	s_mul_i32 s25, s22, 4096
	s_add_u32 s24, s24, s25
	s_lshl_b32 s25, s23, 2
	s_add_u32 s24, s24, s25
	s_add_u32 s26, s56, s24
	s_addc_u32 s27, s57, 0
	s_mov_b32 s29, 0x1000
	s_mov_b32 s8, s26
	s_mov_b32 s9, s27
	s_mov_b32 s7, 0
	s_mov_b32 s30, s23
	s_mul_i32 s30, s30, 5632
	s_mul_i32 s24, s21, 0x1080000
	s_add_u32 s30, s30, s24
	s_lshl_b32 s24, s22, 1
	s_add_u32 s30, s30, s24
	s_add_u32 s30, s30, 0x3800000
	s_add_u32 s4, s36, s30
	s_addc_u32 s5, s37, 0
	s_mov_b32 s6, 0x1600
.Lp0_go_9:
	v_lshlrev_b32_e32 v6, 4, v2
	v_mad_u32_u24 v6, v1, s29, v6
	s_lshl_b32 s29, s29, 3
	global_load_dwordx4 v[56:59], v6, s[26:27] nt
	s_add_u32 s26, s26, s29
	s_addc_u32 s27, s27, 0
	global_load_dwordx4 v[60:63], v6, s[26:27] nt
	s_add_u32 s26, s26, s29
	s_addc_u32 s27, s27, 0
	global_load_dwordx4 v[64:67], v6, s[26:27] nt
	s_add_u32 s26, s26, s29
	s_addc_u32 s27, s27, 0
	global_load_dwordx4 v[68:71], v6, s[26:27] nt
	s_add_u32 s26, s26, s29
	s_addc_u32 s27, s27, 0
	global_load_dwordx4 v[72:75], v6, s[26:27] nt
	s_add_u32 s26, s26, s29
	s_addc_u32 s27, s27, 0
	global_load_dwordx4 v[76:79], v6, s[26:27] nt
	s_add_u32 s26, s26, s29
	s_addc_u32 s27, s27, 0
	global_load_dwordx4 v[80:83], v6, s[26:27] nt
	s_add_u32 s26, s26, s29
	s_addc_u32 s27, s27, 0
	global_load_dwordx4 v[84:87], v6, s[26:27] nt
	global_load_dwordx4 v[88:91], v5, s[8:9]
	global_load_dwordx4 v[92:95], v5, s[8:9] offset:16
	s_add_u32 s2, s2, s28
	s_cmp_lt_u32 s2, 15040
	s_cselect_b32 s18, 1, 0
	s_cselect_b32 s20, s2, 0
	s_cmp_lt_u32 s20, 10816
	s_cbranch_scc0 .Lp0_ffn_10
	s_cmp_lt_u32 s20, 5408
	s_cselect_b32 s21, 0, 1
	s_cselect_b32 s22, 0, 5408
	s_sub_u32 s20, s20, s22
	s_cmp_lt_u32 s20, 768
	s_cbranch_scc1 .Lp0_k0_12
	s_sub_u32 s20, s20, 768
	s_cmp_lt_u32 s20, 512
	s_cbranch_scc1 .Lp0_k1_13
	s_sub_u32 s20, s20, 512
	s_cmp_lt_u32 s20, 3104
	s_cbranch_scc1 .Lp0_k2_14
	s_sub_u32 s20, s20, 3104
	s_branch .Lp0_k3_15

.Lp0_k0_12:
	s_mul_hi_u32 s22, s20, 0x5555556
	s_mul_i32 s23, s22, 48
	s_sub_u32 s23, s20, s23
	s_lshl_b32 s22, s22, 6
	s_lshl_b32 s23, s23, 5
	s_mul_i32 s24, s21, 0x600000
	s_mul_i32 s25, s22, 6144
	s_add_u32 s24, s24, s25
	s_lshl_b32 s25, s23, 2
	s_add_u32 s24, s24, s25
	s_add_u32 s26, s40, s24
	s_addc_u32 s27, s41, 0
	s_mov_b32 s29, 0x1800
	s_lshl_b32 s24, s21, 12
	s_lshl_b32 s25, s22, 2
	s_add_u32 s24, s24, s25
	s_add_u32 s16, s38, s24
	s_addc_u32 s17, s39, 0
	s_mov_b32 s15, 1
	s_mov_b32 s30, s23
	s_mul_i32 s30, s30, 2048
	s_mul_i32 s24, s21, 0x500000
	s_add_u32 s30, s30, s24
	s_lshl_b32 s24, s22, 1
	s_add_u32 s30, s30, s24
	s_add_u32 s30, s30, 0x200000
	s_add_u32 s12, s36, s30
	s_addc_u32 s13, s37, 0
	s_mov_b32 s14, 0x800
	s_branch .Lp0_go_18
.Lp0_k1_13:
	s_lshr_b32 s22, s20, 5
	s_and_b32 s23, s20, 31
	s_lshl_b32 s22, s22, 6
	s_lshl_b32 s23, s23, 5
	s_mul_i32 s24, s21, 0x400000
	s_mul_i32 s25, s22, 4096
	s_add_u32 s24, s24, s25
	s_lshl_b32 s25, s23, 2
	s_add_u32 s24, s24, s25
	s_add_u32 s26, s42, s24
	s_addc_u32 s27, s43, 0
	s_mov_b32 s29, 0x1000
	s_mov_b32 s16, s26
	s_mov_b32 s17, s27
	s_mov_b32 s15, 0
	s_mov_b32 s30, s23
	s_mul_i32 s30, s30, 2048
	s_mul_i32 s24, s21, 0x500000
	s_add_u32 s30, s30, s24
	s_lshl_b32 s24, s22, 1
	s_add_u32 s30, s30, s24
	s_add_u32 s30, s30, 0x500000
	s_add_u32 s12, s36, s30
	s_addc_u32 s13, s37, 0
	s_mov_b32 s14, 0x800
	s_branch .Lp0_go_18
.Lp0_k2_14:
	s_mul_hi_u32 s22, s20, 0x151d07f
	s_mul_i32 s23, s22, 194
	s_sub_u32 s23, s20, s23
	s_lshl_b32 s22, s22, 6
	s_lshl_b32 s23, s23, 5
	s_mul_i32 s24, s21, 0x1840000
	s_mul_i32 s25, s22, 24832
	s_add_u32 s24, s24, s25
	s_lshl_b32 s25, s23, 2
	s_add_u32 s24, s24, s25
	s_add_u32 s26, s48, s24
	s_addc_u32 s27, s49, 0
	s_mov_b32 s29, 0x6100
	s_lshl_b32 s24, s21, 12
	s_lshl_b32 s25, s22, 2
	s_add_u32 s24, s24, s25
	s_add_u32 s16, s44, s24
	s_addc_u32 s17, s45, 0
	s_mov_b32 s15, 1
	s_mov_b32 s30, s23
	s_mul_i32 s30, s30, 2048
	s_mul_i32 s24, s21, 0x1080000
	s_add_u32 s30, s30, s24
	s_lshl_b32 s24, s22, 1
	s_add_u32 s30, s30, s24
	s_add_u32 s30, s30, 0xc00000
	s_add_u32 s12, s36, s30
	s_addc_u32 s13, s37, 0
	s_mov_b32 s14, 0x800
	s_branch .Lp0_go_18
.Lp0_k3_15:
	s_lshr_b32 s22, s20, 5
	s_and_b32 s23, s20, 31
	s_lshl_b32 s22, s22, 6
	s_lshl_b32 s23, s23, 5
	s_mul_i32 s24, s21, 0x800000
	s_mul_i32 s25, s22, 4096
	s_add_u32 s24, s24, s25
	s_lshl_b32 s25, s23, 2
	s_add_u32 s24, s24, s25
	s_add_u32 s26, s50, s24
	s_addc_u32 s27, s51, 0
	s_mov_b32 s29, 0x1000
	s_mov_b32 s16, s26
	s_mov_b32 s17, s27
	s_mov_b32 s15, 0
	s_mov_b32 s30, s23
	s_mul_i32 s30, s30, 4096
	s_mul_i32 s24, s21, 0x1080000
	s_add_u32 s30, s30, s24
	s_lshl_b32 s24, s22, 1
	s_add_u32 s30, s30, s24
	s_add_u32 s30, s30, 0x1880000
	s_add_u32 s12, s36, s30
	s_addc_u32 s13, s37, 0
	s_mov_b32 s14, 0x1000
	s_branch .Lp0_go_18
.Lp0_k4_16:
	s_mul_hi_u32 s22, s20, 0x1745d18
	s_mul_i32 s23, s22, 176
	s_sub_u32 s23, s20, s23
	s_lshl_b32 s22, s22, 6
	s_lshl_b32 s23, s23, 5
	s_mul_i32 s24, s21, 0x1600000
	s_mul_i32 s25, s22, 22528
	s_add_u32 s24, s24, s25
	s_lshl_b32 s25, s23, 2
	s_add_u32 s24, s24, s25
	s_add_u32 s26, s54, s24
	s_addc_u32 s27, s55, 0
	s_mov_b32 s29, 0x5800
	s_lshl_b32 s24, s21, 12
	s_lshl_b32 s25, s22, 2
	s_add_u32 s24, s24, s25
	s_add_u32 s16, s52, s24
	s_addc_u32 s17, s53, 0
	s_mov_b32 s15, 1
	s_cmp_lt_u32 s23, 2816
	s_cselect_b32 s24, 0, 2816
	s_cselect_b32 s25, 0, 128
	s_sub_u32 s24, s23, s24
	s_lshr_b32 s30, s24, 7
	s_lshl_b32 s30, s30, 8
	s_and_b32 s24, s24, 127
	s_add_u32 s30, s30, s24
	s_add_u32 s30, s30, s25
	s_mul_i32 s30, s30, 2048
	s_mul_i32 s24, s21, 0x1080000
	s_add_u32 s30, s30, s24
	s_lshl_b32 s24, s22, 1
	s_add_u32 s30, s30, s24
	s_add_u32 s30, s30, 0x2d00000
	s_add_u32 s12, s36, s30
	s_addc_u32 s13, s37, 0
	s_mov_b32 s14, 0x800
	s_branch .Lp0_go_18
.Lp0_k5_17:
	s_lshr_b32 s22, s20, 5
	s_and_b32 s23, s20, 31
	s_lshl_b32 s22, s22, 6
	s_lshl_b32 s23, s23, 5
	s_mul_i32 s24, s21, 0xb00000
	s_mul_i32 s25, s22, 4096
	s_add_u32 s24, s24, s25
	s_lshl_b32 s25, s23, 2
	s_add_u32 s24, s24, s25
	s_add_u32 s26, s56, s24
	s_addc_u32 s27, s57, 0
	s_mov_b32 s29, 0x1000
	s_mov_b32 s16, s26
	s_mov_b32 s17, s27
	s_mov_b32 s15, 0
	s_mov_b32 s30, s23
	s_mul_i32 s30, s30, 5632
	s_mul_i32 s24, s21, 0x1080000
	s_add_u32 s30, s30, s24
	s_lshl_b32 s24, s22, 1
	s_add_u32 s30, s30, s24
	s_add_u32 s30, s30, 0x3800000
	s_add_u32 s12, s36, s30
	s_addc_u32 s13, s37, 0
	s_mov_b32 s14, 0x1600
.Lp0_go_18:
	v_lshlrev_b32_e32 v6, 4, v2
	v_mad_u32_u24 v6, v1, s29, v6
	s_lshl_b32 s29, s29, 3
	global_load_dwordx4 v[96:99], v6, s[26:27] nt
	s_add_u32 s26, s26, s29
	s_addc_u32 s27, s27, 0
	global_load_dwordx4 v[100:103], v6, s[26:27] nt
	s_add_u32 s26, s26, s29
	s_addc_u32 s27, s27, 0
	global_load_dwordx4 v[104:107], v6, s[26:27] nt
	s_add_u32 s26, s26, s29
	s_addc_u32 s27, s27, 0
	global_load_dwordx4 v[108:111], v6, s[26:27] nt
	s_add_u32 s26, s26, s29
	s_addc_u32 s27, s27, 0
	global_load_dwordx4 v[112:115], v6, s[26:27] nt
	s_add_u32 s26, s26, s29
	s_addc_u32 s27, s27, 0
	global_load_dwordx4 v[116:119], v6, s[26:27] nt
	s_add_u32 s26, s26, s29
	s_addc_u32 s27, s27, 0
	global_load_dwordx4 v[120:123], v6, s[26:27] nt
	s_add_u32 s26, s26, s29
	s_addc_u32 s27, s27, 0
	global_load_dwordx4 v[124:127], v6, s[26:27] nt
	global_load_dwordx4 v[128:131], v5, s[16:17]
	global_load_dwordx4 v[132:135], v5, s[16:17] offset:16
	s_cmp_eq_u32 s10, 0
	s_cbranch_scc1 .Lp0_exit
	s_waitcnt vmcnt(10)
	ds_write_b32 v3, v56 offset:0
	ds_write_b32 v3, v57 offset:4
	ds_write_b32 v3, v58 offset:8
	ds_write_b32 v3, v59 offset:12
	ds_write_b32 v3, v60 offset:1056
	ds_write_b32 v3, v61 offset:1060
	ds_write_b32 v3, v62 offset:1064
	ds_write_b32 v3, v63 offset:1068
	ds_write_b32 v3, v64 offset:2112
	ds_write_b32 v3, v65 offset:2116
	ds_write_b32 v3, v66 offset:2120
	ds_write_b32 v3, v67 offset:2124
	ds_write_b32 v3, v68 offset:3168
	ds_write_b32 v3, v69 offset:3172
	ds_write_b32 v3, v70 offset:3176
	ds_write_b32 v3, v71 offset:3180
	ds_write_b32 v3, v72 offset:4224
	ds_write_b32 v3, v73 offset:4228
	ds_write_b32 v3, v74 offset:4232
	ds_write_b32 v3, v75 offset:4236
	ds_write_b32 v3, v76 offset:5280
	ds_write_b32 v3, v77 offset:5284
	ds_write_b32 v3, v78 offset:5288
	ds_write_b32 v3, v79 offset:5292
	ds_write_b32 v3, v80 offset:6336
	ds_write_b32 v3, v81 offset:6340
	ds_write_b32 v3, v82 offset:6344
	ds_write_b32 v3, v83 offset:6348
	ds_write_b32 v3, v84 offset:7392
	ds_write_b32 v3, v85 offset:7396
	ds_write_b32 v3, v86 offset:7400
	ds_write_b32 v3, v87 offset:7404
	v_lshlrev_b32_e32 v7, 4, v1
	v_mad_u32_u24 v7, v2, s6, v7
	s_lshl_b32 s20, s6, 3
	s_waitcnt lgkmcnt(0)
	ds_read2_b32 v[16:17], v4 offset0:0 offset1:33
	ds_read2_b32 v[18:19], v4 offset0:66 offset1:99
	ds_read2_b32 v[20:21], v4 offset0:132 offset1:165
	ds_read2_b32 v[22:23], v4 offset0:198 offset1:231
	ds_read2_b32 v[24:25], v4 offset0:8 offset1:41
	ds_read2_b32 v[26:27], v4 offset0:74 offset1:107
	ds_read2_b32 v[28:29], v4 offset0:140 offset1:173
	ds_read2_b32 v[30:31], v4 offset0:206 offset1:239
	ds_read2_b32 v[32:33], v4 offset0:16 offset1:49
	ds_read2_b32 v[34:35], v4 offset0:82 offset1:115
	ds_read2_b32 v[36:37], v4 offset0:148 offset1:181
	ds_read2_b32 v[38:39], v4 offset0:214 offset1:247
	ds_read2_b32 v[40:41], v4 offset0:24 offset1:57
	ds_read2_b32 v[42:43], v4 offset0:90 offset1:123
	ds_read2_b32 v[44:45], v4 offset0:156 offset1:189
	ds_read2_b32 v[46:47], v4 offset0:222 offset1:255
	s_cmp_eq_u32 s7, 0
	s_waitcnt lgkmcnt(0)
	s_cbranch_scc1 .Lp0_nog_19
	v_mul_f32_e32 v16, v16, v88
	v_mul_f32_e32 v17, v17, v89
	v_mul_f32_e32 v18, v18, v90
	v_mul_f32_e32 v19, v19, v91
	v_mul_f32_e32 v20, v20, v92
	v_mul_f32_e32 v21, v21, v93
	v_mul_f32_e32 v22, v22, v94
	v_mul_f32_e32 v23, v23, v95
	v_mul_f32_e32 v24, v24, v88
	v_mul_f32_e32 v25, v25, v89
	v_mul_f32_e32 v26, v26, v90
	v_mul_f32_e32 v27, v27, v91
	v_mul_f32_e32 v28, v28, v92
	v_mul_f32_e32 v29, v29, v93
	v_mul_f32_e32 v30, v30, v94
	v_mul_f32_e32 v31, v31, v95
	v_mul_f32_e32 v32, v32, v88
	v_mul_f32_e32 v33, v33, v89
	v_mul_f32_e32 v34, v34, v90
	v_mul_f32_e32 v35, v35, v91
	v_mul_f32_e32 v36, v36, v92
	v_mul_f32_e32 v37, v37, v93
	v_mul_f32_e32 v38, v38, v94
	v_mul_f32_e32 v39, v39, v95
	v_mul_f32_e32 v40, v40, v88
	v_mul_f32_e32 v41, v41, v89
	v_mul_f32_e32 v42, v42, v90
	v_mul_f32_e32 v43, v43, v91
	v_mul_f32_e32 v44, v44, v92
	v_mul_f32_e32 v45, v45, v93
	v_mul_f32_e32 v46, v46, v94
	v_mul_f32_e32 v47, v47, v95
.Lp0_nog_19:
	v_cvt_pk_bf16_f32 v136, v16, v17
	v_cvt_pk_bf16_f32 v137, v18, v19
	v_cvt_pk_bf16_f32 v138, v20, v21
	v_cvt_pk_bf16_f32 v139, v22, v23
	v_cvt_pk_bf16_f32 v140, v24, v25
	v_cvt_pk_bf16_f32 v141, v26, v27
	v_cvt_pk_bf16_f32 v142, v28, v29
	v_cvt_pk_bf16_f32 v143, v30, v31
	v_cvt_pk_bf16_f32 v144, v32, v33
	v_cvt_pk_bf16_f32 v145, v34, v35
	v_cvt_pk_bf16_f32 v146, v36, v37
	v_cvt_pk_bf16_f32 v147, v38, v39
	v_cvt_pk_bf16_f32 v148, v40, v41
	v_cvt_pk_bf16_f32 v149, v42, v43
	v_cvt_pk_bf16_f32 v150, v44, v45
	v_cvt_pk_bf16_f32 v151, v46, v47
	global_store_dwordx4 v7, v[136:139], s[4:5]
	s_add_u32 s4, s4, s20
	s_addc_u32 s5, s5, 0
	global_store_dwordx4 v7, v[140:143], s[4:5]
	s_add_u32 s4, s4, s20
	s_addc_u32 s5, s5, 0
	global_store_dwordx4 v7, v[144:147], s[4:5]
	s_add_u32 s4, s4, s20
	s_addc_u32 s5, s5, 0
	global_store_dwordx4 v7, v[148:151], s[4:5]
.Lp0_loop:
	s_add_u32 s2, s2, s28
	s_cmp_lt_u32 s2, 15040
	s_cselect_b32 s10, 1, 0
	s_cselect_b32 s20, s2, 0
	s_cmp_lt_u32 s20, 10816
	s_cbranch_scc0 .Lp0_ffn_20
	s_cmp_lt_u32 s20, 5408
	s_cselect_b32 s21, 0, 1
	s_cselect_b32 s22, 0, 5408
	s_sub_u32 s20, s20, s22
	s_cmp_lt_u32 s20, 768
	s_cbranch_scc1 .Lp0_k0_22
	s_sub_u32 s20, s20, 768
	s_cmp_lt_u32 s20, 512
	s_cbranch_scc1 .Lp0_k1_23
	s_sub_u32 s20, s20, 512
	s_cmp_lt_u32 s20, 3104
	s_cbranch_scc1 .Lp0_k2_24
	s_sub_u32 s20, s20, 3104
	s_branch .Lp0_k3_25

.Lp0_go_28:
	v_lshlrev_b32_e32 v6, 4, v2
	v_mad_u32_u24 v6, v1, s29, v6
	s_lshl_b32 s29, s29, 3
	global_load_dwordx4 v[56:59], v6, s[26:27] nt
	s_add_u32 s26, s26, s29
	s_addc_u32 s27, s27, 0
	global_load_dwordx4 v[60:63], v6, s[26:27] nt
	s_add_u32 s26, s26, s29
	s_addc_u32 s27, s27, 0
	global_load_dwordx4 v[64:67], v6, s[26:27] nt
	s_add_u32 s26, s26, s29
	s_addc_u32 s27, s27, 0
	global_load_dwordx4 v[68:71], v6, s[26:27] nt
	s_add_u32 s26, s26, s29
	s_addc_u32 s27, s27, 0
	global_load_dwordx4 v[72:75], v6, s[26:27] nt
	s_add_u32 s26, s26, s29
	s_addc_u32 s27, s27, 0
	global_load_dwordx4 v[76:79], v6, s[26:27] nt
	s_add_u32 s26, s26, s29
	s_addc_u32 s27, s27, 0
	global_load_dwordx4 v[80:83], v6, s[26:27] nt
	s_add_u32 s26, s26, s29
	s_addc_u32 s27, s27, 0
	global_load_dwordx4 v[84:87], v6, s[26:27] nt
	global_load_dwordx4 v[88:91], v5, s[8:9]
	global_load_dwordx4 v[92:95], v5, s[8:9] offset:16
	s_cmp_eq_u32 s18, 0
	s_cbranch_scc1 .Lp0_exit
	s_waitcnt vmcnt(14)
	ds_write_b32 v3, v96 offset:0
	ds_write_b32 v3, v97 offset:4
	ds_write_b32 v3, v98 offset:8
	ds_write_b32 v3, v99 offset:12
	ds_write_b32 v3, v100 offset:1056
	ds_write_b32 v3, v101 offset:1060
	ds_write_b32 v3, v102 offset:1064
	ds_write_b32 v3, v103 offset:1068
	ds_write_b32 v3, v104 offset:2112
	ds_write_b32 v3, v105 offset:2116
	ds_write_b32 v3, v106 offset:2120
	ds_write_b32 v3, v107 offset:2124
	ds_write_b32 v3, v108 offset:3168
	ds_write_b32 v3, v109 offset:3172
	ds_write_b32 v3, v110 offset:3176
	ds_write_b32 v3, v111 offset:3180
	ds_write_b32 v3, v112 offset:4224
	ds_write_b32 v3, v113 offset:4228
	ds_write_b32 v3, v114 offset:4232
	ds_write_b32 v3, v115 offset:4236
	ds_write_b32 v3, v116 offset:5280
	ds_write_b32 v3, v117 offset:5284
	ds_write_b32 v3, v118 offset:5288
	ds_write_b32 v3, v119 offset:5292
	ds_write_b32 v3, v120 offset:6336
	ds_write_b32 v3, v121 offset:6340
	ds_write_b32 v3, v122 offset:6344
	ds_write_b32 v3, v123 offset:6348
	ds_write_b32 v3, v124 offset:7392
	ds_write_b32 v3, v125 offset:7396
	ds_write_b32 v3, v126 offset:7400
	ds_write_b32 v3, v127 offset:7404
	v_lshlrev_b32_e32 v7, 4, v1
	v_mad_u32_u24 v7, v2, s14, v7
	s_lshl_b32 s20, s14, 3
	s_waitcnt lgkmcnt(0)
	ds_read2_b32 v[16:17], v4 offset0:0 offset1:33
	ds_read2_b32 v[18:19], v4 offset0:66 offset1:99
	ds_read2_b32 v[20:21], v4 offset0:132 offset1:165
	ds_read2_b32 v[22:23], v4 offset0:198 offset1:231
	ds_read2_b32 v[24:25], v4 offset0:8 offset1:41
	ds_read2_b32 v[26:27], v4 offset0:74 offset1:107
	ds_read2_b32 v[28:29], v4 offset0:140 offset1:173
	ds_read2_b32 v[30:31], v4 offset0:206 offset1:239
	ds_read2_b32 v[32:33], v4 offset0:16 offset1:49
	ds_read2_b32 v[34:35], v4 offset0:82 offset1:115
	ds_read2_b32 v[36:37], v4 offset0:148 offset1:181
	ds_read2_b32 v[38:39], v4 offset0:214 offset1:247
	ds_read2_b32 v[40:41], v4 offset0:24 offset1:57
	ds_read2_b32 v[42:43], v4 offset0:90 offset1:123
	ds_read2_b32 v[44:45], v4 offset0:156 offset1:189
	ds_read2_b32 v[46:47], v4 offset0:222 offset1:255
	s_cmp_eq_u32 s15, 0
	s_waitcnt lgkmcnt(0)
	s_cbranch_scc1 .Lp0_nog_29
	v_mul_f32_e32 v16, v16, v128
	v_mul_f32_e32 v17, v17, v129
	v_mul_f32_e32 v18, v18, v130
	v_mul_f32_e32 v19, v19, v131
	v_mul_f32_e32 v20, v20, v132
	v_mul_f32_e32 v21, v21, v133
	v_mul_f32_e32 v22, v22, v134
	v_mul_f32_e32 v23, v23, v135
	v_mul_f32_e32 v24, v24, v128
	v_mul_f32_e32 v25, v25, v129
	v_mul_f32_e32 v26, v26, v130
	v_mul_f32_e32 v27, v27, v131
	v_mul_f32_e32 v28, v28, v132
	v_mul_f32_e32 v29, v29, v133
	v_mul_f32_e32 v30, v30, v134
	v_mul_f32_e32 v31, v31, v135
	v_mul_f32_e32 v32, v32, v128
	v_mul_f32_e32 v33, v33, v129
	v_mul_f32_e32 v34, v34, v130
	v_mul_f32_e32 v35, v35, v131
	v_mul_f32_e32 v36, v36, v132
	v_mul_f32_e32 v37, v37, v133
	v_mul_f32_e32 v38, v38, v134
	v_mul_f32_e32 v39, v39, v135
	v_mul_f32_e32 v40, v40, v128
	v_mul_f32_e32 v41, v41, v129
	v_mul_f32_e32 v42, v42, v130
	v_mul_f32_e32 v43, v43, v131
	v_mul_f32_e32 v44, v44, v132
	v_mul_f32_e32 v45, v45, v133
	v_mul_f32_e32 v46, v46, v134
	v_mul_f32_e32 v47, v47, v135
.Lp0_nog_29:
	v_cvt_pk_bf16_f32 v136, v16, v17
	v_cvt_pk_bf16_f32 v137, v18, v19
	v_cvt_pk_bf16_f32 v138, v20, v21
	v_cvt_pk_bf16_f32 v139, v22, v23
	v_cvt_pk_bf16_f32 v140, v24, v25
	v_cvt_pk_bf16_f32 v141, v26, v27
	v_cvt_pk_bf16_f32 v142, v28, v29
	v_cvt_pk_bf16_f32 v143, v30, v31
	v_cvt_pk_bf16_f32 v144, v32, v33
	v_cvt_pk_bf16_f32 v145, v34, v35
	v_cvt_pk_bf16_f32 v146, v36, v37
	v_cvt_pk_bf16_f32 v147, v38, v39
	v_cvt_pk_bf16_f32 v148, v40, v41
	v_cvt_pk_bf16_f32 v149, v42, v43
	v_cvt_pk_bf16_f32 v150, v44, v45
	v_cvt_pk_bf16_f32 v151, v46, v47
	global_store_dwordx4 v7, v[136:139], s[12:13]
	s_add_u32 s12, s12, s20
	s_addc_u32 s13, s13, 0
	global_store_dwordx4 v7, v[140:143], s[12:13]
	s_add_u32 s12, s12, s20
	s_addc_u32 s13, s13, 0
	global_store_dwordx4 v7, v[144:147], s[12:13]
	s_add_u32 s12, s12, s20
	s_addc_u32 s13, s13, 0
	global_store_dwordx4 v7, v[148:151], s[12:13]
	s_add_u32 s2, s2, s28
	s_cmp_lt_u32 s2, 15040
	s_cselect_b32 s18, 1, 0
	s_cselect_b32 s20, s2, 0
	s_cmp_lt_u32 s20, 10816
	s_cbranch_scc0 .Lp0_ffn_30
	s_cmp_lt_u32 s20, 5408
	s_cselect_b32 s21, 0, 1
	s_cselect_b32 s22, 0, 5408
	s_sub_u32 s20, s20, s22
	s_cmp_lt_u32 s20, 768
	s_cbranch_scc1 .Lp0_k0_32
	s_sub_u32 s20, s20, 768
	s_cmp_lt_u32 s20, 512
	s_cbranch_scc1 .Lp0_k1_33
	s_sub_u32 s20, s20, 512
	s_cmp_lt_u32 s20, 3104
	s_cbranch_scc1 .Lp0_k2_34
	s_sub_u32 s20, s20, 3104
	s_branch .Lp0_k3_35

.Lp0_go_38:
	v_lshlrev_b32_e32 v6, 4, v2
	v_mad_u32_u24 v6, v1, s29, v6
	s_lshl_b32 s29, s29, 3
	global_load_dwordx4 v[96:99], v6, s[26:27] nt
	s_add_u32 s26, s26, s29
	s_addc_u32 s27, s27, 0
	global_load_dwordx4 v[100:103], v6, s[26:27] nt
	s_add_u32 s26, s26, s29
	s_addc_u32 s27, s27, 0
	global_load_dwordx4 v[104:107], v6, s[26:27] nt
	s_add_u32 s26, s26, s29
	s_addc_u32 s27, s27, 0
	global_load_dwordx4 v[108:111], v6, s[26:27] nt
	s_add_u32 s26, s26, s29
	s_addc_u32 s27, s27, 0
	global_load_dwordx4 v[112:115], v6, s[26:27] nt
	s_add_u32 s26, s26, s29
	s_addc_u32 s27, s27, 0
	global_load_dwordx4 v[116:119], v6, s[26:27] nt
	s_add_u32 s26, s26, s29
	s_addc_u32 s27, s27, 0
	global_load_dwordx4 v[120:123], v6, s[26:27] nt
	s_add_u32 s26, s26, s29
	s_addc_u32 s27, s27, 0
	global_load_dwordx4 v[124:127], v6, s[26:27] nt
	global_load_dwordx4 v[128:131], v5, s[16:17]
	global_load_dwordx4 v[132:135], v5, s[16:17] offset:16
	s_cmp_eq_u32 s10, 0
	s_cbranch_scc1 .Lp0_exit
	s_waitcnt vmcnt(14)
	ds_write_b32 v3, v56 offset:0
	ds_write_b32 v3, v57 offset:4
	ds_write_b32 v3, v58 offset:8
	ds_write_b32 v3, v59 offset:12
	ds_write_b32 v3, v60 offset:1056
	ds_write_b32 v3, v61 offset:1060
	ds_write_b32 v3, v62 offset:1064
	ds_write_b32 v3, v63 offset:1068
	ds_write_b32 v3, v64 offset:2112
	ds_write_b32 v3, v65 offset:2116
	ds_write_b32 v3, v66 offset:2120
	ds_write_b32 v3, v67 offset:2124
	ds_write_b32 v3, v68 offset:3168
	ds_write_b32 v3, v69 offset:3172
	ds_write_b32 v3, v70 offset:3176
	ds_write_b32 v3, v71 offset:3180
	ds_write_b32 v3, v72 offset:4224
	ds_write_b32 v3, v73 offset:4228
	ds_write_b32 v3, v74 offset:4232
	ds_write_b32 v3, v75 offset:4236
	ds_write_b32 v3, v76 offset:5280
	ds_write_b32 v3, v77 offset:5284
	ds_write_b32 v3, v78 offset:5288
	ds_write_b32 v3, v79 offset:5292
	ds_write_b32 v3, v80 offset:6336
	ds_write_b32 v3, v81 offset:6340
	ds_write_b32 v3, v82 offset:6344
	ds_write_b32 v3, v83 offset:6348
	ds_write_b32 v3, v84 offset:7392
	ds_write_b32 v3, v85 offset:7396
	ds_write_b32 v3, v86 offset:7400
	ds_write_b32 v3, v87 offset:7404
	v_lshlrev_b32_e32 v7, 4, v1
	v_mad_u32_u24 v7, v2, s6, v7
	s_lshl_b32 s20, s6, 3
	s_waitcnt lgkmcnt(0)
	ds_read2_b32 v[16:17], v4 offset0:0 offset1:33
	ds_read2_b32 v[18:19], v4 offset0:66 offset1:99
	ds_read2_b32 v[20:21], v4 offset0:132 offset1:165
	ds_read2_b32 v[22:23], v4 offset0:198 offset1:231
	ds_read2_b32 v[24:25], v4 offset0:8 offset1:41
	ds_read2_b32 v[26:27], v4 offset0:74 offset1:107
	ds_read2_b32 v[28:29], v4 offset0:140 offset1:173
	ds_read2_b32 v[30:31], v4 offset0:206 offset1:239
	ds_read2_b32 v[32:33], v4 offset0:16 offset1:49
	ds_read2_b32 v[34:35], v4 offset0:82 offset1:115
	ds_read2_b32 v[36:37], v4 offset0:148 offset1:181
	ds_read2_b32 v[38:39], v4 offset0:214 offset1:247
	ds_read2_b32 v[40:41], v4 offset0:24 offset1:57
	ds_read2_b32 v[42:43], v4 offset0:90 offset1:123
	ds_read2_b32 v[44:45], v4 offset0:156 offset1:189
	ds_read2_b32 v[46:47], v4 offset0:222 offset1:255
	s_cmp_eq_u32 s7, 0
	s_waitcnt lgkmcnt(0)
	s_cbranch_scc1 .Lp0_nog_39
	v_mul_f32_e32 v16, v16, v88
	v_mul_f32_e32 v17, v17, v89
	v_mul_f32_e32 v18, v18, v90
	v_mul_f32_e32 v19, v19, v91
	v_mul_f32_e32 v20, v20, v92
	v_mul_f32_e32 v21, v21, v93
	v_mul_f32_e32 v22, v22, v94
	v_mul_f32_e32 v23, v23, v95
	v_mul_f32_e32 v24, v24, v88
	v_mul_f32_e32 v25, v25, v89
	v_mul_f32_e32 v26, v26, v90
	v_mul_f32_e32 v27, v27, v91
	v_mul_f32_e32 v28, v28, v92
	v_mul_f32_e32 v29, v29, v93
	v_mul_f32_e32 v30, v30, v94
	v_mul_f32_e32 v31, v31, v95
	v_mul_f32_e32 v32, v32, v88
	v_mul_f32_e32 v33, v33, v89
	v_mul_f32_e32 v34, v34, v90
	v_mul_f32_e32 v35, v35, v91
	v_mul_f32_e32 v36, v36, v92
	v_mul_f32_e32 v37, v37, v93
	v_mul_f32_e32 v38, v38, v94
	v_mul_f32_e32 v39, v39, v95
	v_mul_f32_e32 v40, v40, v88
	v_mul_f32_e32 v41, v41, v89
	v_mul_f32_e32 v42, v42, v90
	v_mul_f32_e32 v43, v43, v91
	v_mul_f32_e32 v44, v44, v92
	v_mul_f32_e32 v45, v45, v93
	v_mul_f32_e32 v46, v46, v94
	v_mul_f32_e32 v47, v47, v95
.Lp0_nog_39:
	v_cvt_pk_bf16_f32 v136, v16, v17
	v_cvt_pk_bf16_f32 v137, v18, v19
	v_cvt_pk_bf16_f32 v138, v20, v21
	v_cvt_pk_bf16_f32 v139, v22, v23
	v_cvt_pk_bf16_f32 v140, v24, v25
	v_cvt_pk_bf16_f32 v141, v26, v27
	v_cvt_pk_bf16_f32 v142, v28, v29
	v_cvt_pk_bf16_f32 v143, v30, v31
	v_cvt_pk_bf16_f32 v144, v32, v33
	v_cvt_pk_bf16_f32 v145, v34, v35
	v_cvt_pk_bf16_f32 v146, v36, v37
	v_cvt_pk_bf16_f32 v147, v38, v39
	v_cvt_pk_bf16_f32 v148, v40, v41
	v_cvt_pk_bf16_f32 v149, v42, v43
	v_cvt_pk_bf16_f32 v150, v44, v45
	v_cvt_pk_bf16_f32 v151, v46, v47
	global_store_dwordx4 v7, v[136:139], s[4:5]
	s_add_u32 s4, s4, s20
	s_addc_u32 s5, s5, 0
	global_store_dwordx4 v7, v[140:143], s[4:5]
	s_add_u32 s4, s4, s20
	s_addc_u32 s5, s5, 0
	global_store_dwordx4 v7, v[144:147], s[4:5]
	s_add_u32 s4, s4, s20
	s_addc_u32 s5, s5, 0
	global_store_dwordx4 v7, v[148:151], s[4:5]
	s_branch .Lp0_loop
.Lp0_exit:
	s_waitcnt vmcnt(0)
	v_writelane_b32 v253, s3, 5
	s_mov_b32 s31, s3
	s_mov_b32 s35, 0

.Lm_setup_done_3:
	v_lshlrev_b32_e32 v130, 4, v175
	v_add_u32_e32 v130, 0x1e800, v130
	ds_write_b128 v130, v[112:115] offset:0
	ds_write_b128 v130, v[112:115] offset:8192
	s_mov_b32 s14, 0
	s_movk_i32 s16, 1280
	s_movk_i32 s17, 2560
	s_mov_b32 s19, 0
	s_movk_i32 s20, 0x200
	s_cmp_lt_u32 s3, 4
	s_cbranch_scc0 .Lm_pro_hi_6
	s_cmp_eq_u32 s52, 1
	s_cbranch_scc0 .Lm_ys0_8
	v_and_b32_e32 v132, 63, v175
	v_lshlrev_b32_e32 v132, 9, v132
	global_load_dword v146, v132, s[42:43]
	global_load_dword v147, v132, s[42:43] offset:256
	s_add_u32 s42, s42, s48
	s_addc_u32 s43, s43, s55

.LBB0_800:
	s_mov_b64 exec, -1
	s_lshl_b32 s4, s86, 4
	s_add_u32 s4, s60, s4
	s_addc_u32 s5, s61, 0
	s_load_dwordx4 s[8:11], s[4:5], 0xc0
	v_readlane_b32 s6, v253, 3
	s_waitcnt lgkmcnt(0)
	s_cmp_eq_u32 s8, 0
	s_cbranch_scc0 .Ldf_done
	s_cmp_eq_u32 s10, 4
	s_cbranch_scc0 .Ldf_done
	s_cmp_lt_u32 s9, 3
	s_cbranch_scc0 .Ldf_done
	s_movk_i32 s7, 0xb58
.Ldf_mod_1:
	s_cmp_ge_u32 s7, s6
	s_cselect_b32 s4, s6, 0
	s_sub_u32 s7, s7, s4
	s_cmp_ge_u32 s7, s6
	s_cbranch_scc1 .Ldf_mod_1
	s_cmp_eq_u32 s7, 0
	s_cbranch_scc1 .Ldf_done
	s_cmp_ge_u32 s31, s7
	s_cbranch_scc0 .Ldf_done
	s_waitcnt vmcnt(0) lgkmcnt(0)
	s_barrier
	v_writelane_b32 v255, s96, 7
	v_writelane_b32 v255, s97, 8
	v_writelane_b32 v255, s98, 9
	v_writelane_b32 v255, s99, 10
	v_writelane_b32 v255, s86, 0
	v_writelane_b32 v255, s87, 1
	v_writelane_b32 v255, s42, 11
	v_writelane_b32 v255, s43, 12
	s_add_u32 s48, s9, 1
	s_mov_b32 s50, s7
	s_load_dwordx2 s[42:43], s[60:61], 0x80
	s_load_dwordx2 s[44:45], s[60:61], 0x88
	s_load_dwordx2 s[46:47], s[60:61], 0xa0
	s_movk_i32 s49, 0x1080
	v_lshrrev_b32_e32 v8, 6, v175
	v_and_b32_e32 v9, 63, v175
	v_lshrrev_b32_e32 v1, 3, v9
	v_and_b32_e32 v2, 7, v9
	v_readfirstlane_b32 s21, v8
	v_lshlrev_b32_e32 v5, 5, v1
	v_lshlrev_b32_e32 v10, 14, v8
	v_mul_u32_u24_e32 v11, 33, v1
	v_lshl_add_u32 v11, v2, 2, v11
	v_lshl_add_u32 v3, v11, 2, v10
	v_mul_u32_u24_e32 v11, 264, v1
	v_add_u32_e32 v11, v11, v2
	v_lshl_add_u32 v4, v11, 2, v10
	s_sub_u32 s3, s31, s50
	s_lshl_b32 s3, s3, 3
	s_add_u32 s3, s3, s21
	s_sub_u32 s41, s6, s50
	s_lshl_b32 s41, s41, 3
	s_waitcnt lgkmcnt(0)
	s_cmp_lt_u32 s3, s49
	s_cselect_b32 s10, 1, 0
	s_cselect_b32 s21, s3, 0
	s_cmp_lt_u32 s21, 2816
	s_cbranch_scc1 .Ldf_k0_2
	s_sub_u32 s21, s21, 2816
	s_branch .Ldf_k1_3
.Ldf_k0_2:
	s_mul_hi_u32 s23, s21, 0x1745d18
	s_mul_i32 s24, s23, 176
	s_sub_u32 s24, s21, s24
	s_lshl_b32 s23, s23, 6
	s_lshl_b32 s24, s24, 5
	s_mul_i32 s25, s48, 0x1600000
	s_mul_i32 s26, s23, 22528
	s_add_u32 s25, s25, s26
	s_lshl_b32 s26, s24, 2
	s_add_u32 s25, s25, s26
	s_add_u32 s38, s44, s25
	s_addc_u32 s39, s45, 0
	s_mov_b32 s27, 0x5800
	s_lshl_b32 s25, s48, 12
	s_lshl_b32 s26, s23, 2
	s_add_u32 s25, s25, s26
	s_add_u32 s8, s42, s25
	s_addc_u32 s9, s43, 0
	s_mov_b32 s7, 1
	s_cmp_lt_u32 s24, 2816
	s_cselect_b32 s25, 0, 2816
	s_cselect_b32 s26, 0, 128
	s_sub_u32 s25, s24, s25
	s_lshr_b32 s40, s25, 7
	s_lshl_b32 s40, s40, 8
	s_and_b32 s25, s25, 127
	s_add_u32 s40, s40, s25
	s_add_u32 s40, s40, s26
	s_mul_i32 s40, s40, 2048
	s_mul_i32 s25, s48, 0x1080000
	s_add_u32 s40, s40, s25
	s_lshl_b32 s25, s23, 1
	s_add_u32 s40, s40, s25
	s_add_u32 s40, s40, 0x2d00000
	s_add_u32 s4, s36, s40
	s_addc_u32 s5, s37, 0
	s_mov_b32 s6, 0x800
	s_branch .Ldf_go_4
.Ldf_k1_3:
	s_lshr_b32 s23, s21, 5
	s_and_b32 s24, s21, 31
	s_lshl_b32 s23, s23, 6
	s_lshl_b32 s24, s24, 5
	s_mul_i32 s25, s48, 0xb00000
	s_mul_i32 s26, s23, 4096
	s_add_u32 s25, s25, s26
	s_lshl_b32 s26, s24, 2
	s_add_u32 s25, s25, s26
	s_add_u32 s38, s46, s25
	s_addc_u32 s39, s47, 0
	s_mov_b32 s27, 0x1000
	s_mov_b32 s8, s38
	s_mov_b32 s9, s39
	s_mov_b32 s7, 0
	s_mov_b32 s40, s24
	s_mul_i32 s40, s40, 5632
	s_mul_i32 s25, s48, 0x1080000
	s_add_u32 s40, s40, s25
	s_lshl_b32 s25, s23, 1
	s_add_u32 s40, s40, s25
	s_add_u32 s40, s40, 0x3800000
	s_add_u32 s4, s36, s40
	s_addc_u32 s5, s37, 0
	s_mov_b32 s6, 0x1600
.Ldf_go_4:
	v_lshlrev_b32_e32 v6, 4, v2
	v_mad_u32_u24 v6, v1, s27, v6
	s_lshl_b32 s27, s27, 3
	global_load_dwordx4 v[56:59], v6, s[38:39] nt
	s_add_u32 s38, s38, s27
	s_addc_u32 s39, s39, 0
	global_load_dwordx4 v[60:63], v6, s[38:39] nt
	s_add_u32 s38, s38, s27
	s_addc_u32 s39, s39, 0
	global_load_dwordx4 v[64:67], v6, s[38:39] nt
	s_add_u32 s38, s38, s27
	s_addc_u32 s39, s39, 0
	global_load_dwordx4 v[68:71], v6, s[38:39] nt
	s_add_u32 s38, s38, s27
	s_addc_u32 s39, s39, 0
	global_load_dwordx4 v[72:75], v6, s[38:39] nt
	s_add_u32 s38, s38, s27
	s_addc_u32 s39, s39, 0
	global_load_dwordx4 v[76:79], v6, s[38:39] nt
	s_add_u32 s38, s38, s27
	s_addc_u32 s39, s39, 0
	global_load_dwordx4 v[80:83], v6, s[38:39] nt
	s_add_u32 s38, s38, s27
	s_addc_u32 s39, s39, 0
	global_load_dwordx4 v[84:87], v6, s[38:39] nt
	global_load_dwordx4 v[88:91], v5, s[8:9]
	global_load_dwordx4 v[92:95], v5, s[8:9] offset:16
	s_add_u32 s3, s3, s41
	s_cmp_lt_u32 s3, s49
	s_cselect_b32 s20, 1, 0
	s_cselect_b32 s21, s3, 0
	s_cmp_lt_u32 s21, 2816
	s_cbranch_scc1 .Ldf_k0_5
	s_sub_u32 s21, s21, 2816
	s_branch .Ldf_k1_6
.Ldf_k0_5:
	s_mul_hi_u32 s23, s21, 0x1745d18
	s_mul_i32 s24, s23, 176
	s_sub_u32 s24, s21, s24
	s_lshl_b32 s23, s23, 6
	s_lshl_b32 s24, s24, 5
	s_mul_i32 s25, s48, 0x1600000
	s_mul_i32 s26, s23, 22528
	s_add_u32 s25, s25, s26
	s_lshl_b32 s26, s24, 2
	s_add_u32 s25, s25, s26
	s_add_u32 s38, s44, s25
	s_addc_u32 s39, s45, 0
	s_mov_b32 s27, 0x5800
	s_lshl_b32 s25, s48, 12
	s_lshl_b32 s26, s23, 2
	s_add_u32 s25, s25, s26
	s_add_u32 s18, s42, s25
	s_addc_u32 s19, s43, 0
	s_mov_b32 s17, 1
	s_cmp_lt_u32 s24, 2816
	s_cselect_b32 s25, 0, 2816
	s_cselect_b32 s26, 0, 128
	s_sub_u32 s25, s24, s25
	s_lshr_b32 s40, s25, 7
	s_lshl_b32 s40, s40, 8
	s_and_b32 s25, s25, 127
	s_add_u32 s40, s40, s25
	s_add_u32 s40, s40, s26
	s_mul_i32 s40, s40, 2048
	s_mul_i32 s25, s48, 0x1080000
	s_add_u32 s40, s40, s25
	s_lshl_b32 s25, s23, 1
	s_add_u32 s40, s40, s25
	s_add_u32 s40, s40, 0x2d00000
	s_add_u32 s14, s36, s40
	s_addc_u32 s15, s37, 0
	s_mov_b32 s16, 0x800
	s_branch .Ldf_go_7
.Ldf_k1_6:
	s_lshr_b32 s23, s21, 5
	s_and_b32 s24, s21, 31
	s_lshl_b32 s23, s23, 6
	s_lshl_b32 s24, s24, 5
	s_mul_i32 s25, s48, 0xb00000
	s_mul_i32 s26, s23, 4096
	s_add_u32 s25, s25, s26
	s_lshl_b32 s26, s24, 2
	s_add_u32 s25, s25, s26
	s_add_u32 s38, s46, s25
	s_addc_u32 s39, s47, 0
	s_mov_b32 s27, 0x1000
	s_mov_b32 s18, s38
	s_mov_b32 s19, s39
	s_mov_b32 s17, 0
	s_mov_b32 s40, s24
	s_mul_i32 s40, s40, 5632
	s_mul_i32 s25, s48, 0x1080000
	s_add_u32 s40, s40, s25
	s_lshl_b32 s25, s23, 1
	s_add_u32 s40, s40, s25
	s_add_u32 s40, s40, 0x3800000
	s_add_u32 s14, s36, s40
	s_addc_u32 s15, s37, 0
	s_mov_b32 s16, 0x1600
.Ldf_go_7:
	v_lshlrev_b32_e32 v6, 4, v2
	v_mad_u32_u24 v6, v1, s27, v6
	s_lshl_b32 s27, s27, 3
	global_load_dwordx4 v[116:119], v6, s[38:39] nt
	s_add_u32 s38, s38, s27
	s_addc_u32 s39, s39, 0
	global_load_dwordx4 v[120:123], v6, s[38:39] nt
	s_add_u32 s38, s38, s27
	s_addc_u32 s39, s39, 0
	global_load_dwordx4 v[124:127], v6, s[38:39] nt
	s_add_u32 s38, s38, s27
	s_addc_u32 s39, s39, 0
	global_load_dwordx4 v[128:131], v6, s[38:39] nt
	s_add_u32 s38, s38, s27
	s_addc_u32 s39, s39, 0
	global_load_dwordx4 v[132:135], v6, s[38:39] nt
	s_add_u32 s38, s38, s27
	s_addc_u32 s39, s39, 0
	global_load_dwordx4 v[136:139], v6, s[38:39] nt
	s_add_u32 s38, s38, s27
	s_addc_u32 s39, s39, 0
	global_load_dwordx4 v[140:143], v6, s[38:39] nt
	s_add_u32 s38, s38, s27
	s_addc_u32 s39, s39, 0
	global_load_dwordx4 v[144:147], v6, s[38:39] nt
	global_load_dwordx4 v[148:151], v5, s[18:19]
	global_load_dwordx4 v[152:155], v5, s[18:19] offset:16
	s_cmp_eq_u32 s10, 0
	s_cbranch_scc1 .Ldf_exit
	s_waitcnt vmcnt(10)
	ds_write_b32 v3, v56 offset:0
	ds_write_b32 v3, v57 offset:4
	ds_write_b32 v3, v58 offset:8
	ds_write_b32 v3, v59 offset:12
	ds_write_b32 v3, v60 offset:1056
	ds_write_b32 v3, v61 offset:1060
	ds_write_b32 v3, v62 offset:1064
	ds_write_b32 v3, v63 offset:1068
	ds_write_b32 v3, v64 offset:2112
	ds_write_b32 v3, v65 offset:2116
	ds_write_b32 v3, v66 offset:2120
	ds_write_b32 v3, v67 offset:2124
	ds_write_b32 v3, v68 offset:3168
	ds_write_b32 v3, v69 offset:3172
	ds_write_b32 v3, v70 offset:3176
	ds_write_b32 v3, v71 offset:3180
	ds_write_b32 v3, v72 offset:4224
	ds_write_b32 v3, v73 offset:4228
	ds_write_b32 v3, v74 offset:4232
	ds_write_b32 v3, v75 offset:4236
	ds_write_b32 v3, v76 offset:5280
	ds_write_b32 v3, v77 offset:5284
	ds_write_b32 v3, v78 offset:5288
	ds_write_b32 v3, v79 offset:5292
	ds_write_b32 v3, v80 offset:6336
	ds_write_b32 v3, v81 offset:6340
	ds_write_b32 v3, v82 offset:6344
	ds_write_b32 v3, v83 offset:6348
	ds_write_b32 v3, v84 offset:7392
	ds_write_b32 v3, v85 offset:7396
	ds_write_b32 v3, v86 offset:7400
	ds_write_b32 v3, v87 offset:7404
	v_lshlrev_b32_e32 v7, 4, v1
	v_mad_u32_u24 v7, v2, s6, v7
	s_lshl_b32 s21, s6, 3
	s_waitcnt lgkmcnt(0)
	ds_read2_b32 v[16:17], v4 offset0:0 offset1:33
	ds_read2_b32 v[18:19], v4 offset0:66 offset1:99
	ds_read2_b32 v[20:21], v4 offset0:132 offset1:165
	ds_read2_b32 v[22:23], v4 offset0:198 offset1:231
	ds_read2_b32 v[24:25], v4 offset0:8 offset1:41
	ds_read2_b32 v[26:27], v4 offset0:74 offset1:107
	ds_read2_b32 v[28:29], v4 offset0:140 offset1:173
	ds_read2_b32 v[30:31], v4 offset0:206 offset1:239
	ds_read2_b32 v[32:33], v4 offset0:16 offset1:49
	ds_read2_b32 v[34:35], v4 offset0:82 offset1:115
	ds_read2_b32 v[36:37], v4 offset0:148 offset1:181
	ds_read2_b32 v[38:39], v4 offset0:214 offset1:247
	ds_read2_b32 v[40:41], v4 offset0:24 offset1:57
	ds_read2_b32 v[42:43], v4 offset0:90 offset1:123
	ds_read2_b32 v[44:45], v4 offset0:156 offset1:189
	ds_read2_b32 v[46:47], v4 offset0:222 offset1:255
	s_cmp_eq_u32 s7, 0
	s_waitcnt lgkmcnt(0)
	s_cbranch_scc1 .Ldf_nog_8
	v_mul_f32_e32 v16, v16, v88
	v_mul_f32_e32 v17, v17, v89
	v_mul_f32_e32 v18, v18, v90
	v_mul_f32_e32 v19, v19, v91
	v_mul_f32_e32 v20, v20, v92
	v_mul_f32_e32 v21, v21, v93
	v_mul_f32_e32 v22, v22, v94
	v_mul_f32_e32 v23, v23, v95
	v_mul_f32_e32 v24, v24, v88
	v_mul_f32_e32 v25, v25, v89
	v_mul_f32_e32 v26, v26, v90
	v_mul_f32_e32 v27, v27, v91
	v_mul_f32_e32 v28, v28, v92
	v_mul_f32_e32 v29, v29, v93
	v_mul_f32_e32 v30, v30, v94
	v_mul_f32_e32 v31, v31, v95
	v_mul_f32_e32 v32, v32, v88
	v_mul_f32_e32 v33, v33, v89
	v_mul_f32_e32 v34, v34, v90
	v_mul_f32_e32 v35, v35, v91
	v_mul_f32_e32 v36, v36, v92
	v_mul_f32_e32 v37, v37, v93
	v_mul_f32_e32 v38, v38, v94
	v_mul_f32_e32 v39, v39, v95
	v_mul_f32_e32 v40, v40, v88
	v_mul_f32_e32 v41, v41, v89
	v_mul_f32_e32 v42, v42, v90
	v_mul_f32_e32 v43, v43, v91
	v_mul_f32_e32 v44, v44, v92
	v_mul_f32_e32 v45, v45, v93
	v_mul_f32_e32 v46, v46, v94
	v_mul_f32_e32 v47, v47, v95
.Ldf_nog_8:
	v_cvt_pk_bf16_f32 v156, v16, v17
	v_cvt_pk_bf16_f32 v157, v18, v19
	v_cvt_pk_bf16_f32 v158, v20, v21
	v_cvt_pk_bf16_f32 v159, v22, v23
	v_cvt_pk_bf16_f32 v160, v24, v25
	v_cvt_pk_bf16_f32 v161, v26, v27
	v_cvt_pk_bf16_f32 v162, v28, v29
	v_cvt_pk_bf16_f32 v163, v30, v31
	v_cvt_pk_bf16_f32 v164, v32, v33
	v_cvt_pk_bf16_f32 v165, v34, v35
	v_cvt_pk_bf16_f32 v166, v36, v37
	v_cvt_pk_bf16_f32 v167, v38, v39
	v_cvt_pk_bf16_f32 v168, v40, v41
	v_cvt_pk_bf16_f32 v169, v42, v43
	v_cvt_pk_bf16_f32 v170, v44, v45
	v_cvt_pk_bf16_f32 v171, v46, v47
	global_store_dwordx4 v7, v[156:159], s[4:5]
	s_add_u32 s4, s4, s21
	s_addc_u32 s5, s5, 0
	global_store_dwordx4 v7, v[160:163], s[4:5]
	s_add_u32 s4, s4, s21
	s_addc_u32 s5, s5, 0
	global_store_dwordx4 v7, v[164:167], s[4:5]
	s_add_u32 s4, s4, s21
	s_addc_u32 s5, s5, 0
	global_store_dwordx4 v7, v[168:171], s[4:5]
.Ldf_loop:
	s_add_u32 s3, s3, s41
	s_cmp_lt_u32 s3, s49
	s_cselect_b32 s10, 1, 0
	s_cselect_b32 s21, s3, 0
	s_cmp_lt_u32 s21, 2816
	s_cbranch_scc1 .Ldf_k0_9
	s_sub_u32 s21, s21, 2816
	s_branch .Ldf_k1_10

.Ldf_go_11:
	v_lshlrev_b32_e32 v6, 4, v2
	v_mad_u32_u24 v6, v1, s27, v6
	s_lshl_b32 s27, s27, 3
	global_load_dwordx4 v[56:59], v6, s[38:39] nt
	s_add_u32 s38, s38, s27
	s_addc_u32 s39, s39, 0
	global_load_dwordx4 v[60:63], v6, s[38:39] nt
	s_add_u32 s38, s38, s27
	s_addc_u32 s39, s39, 0
	global_load_dwordx4 v[64:67], v6, s[38:39] nt
	s_add_u32 s38, s38, s27
	s_addc_u32 s39, s39, 0
	global_load_dwordx4 v[68:71], v6, s[38:39] nt
	s_add_u32 s38, s38, s27
	s_addc_u32 s39, s39, 0
	global_load_dwordx4 v[72:75], v6, s[38:39] nt
	s_add_u32 s38, s38, s27
	s_addc_u32 s39, s39, 0
	global_load_dwordx4 v[76:79], v6, s[38:39] nt
	s_add_u32 s38, s38, s27
	s_addc_u32 s39, s39, 0
	global_load_dwordx4 v[80:83], v6, s[38:39] nt
	s_add_u32 s38, s38, s27
	s_addc_u32 s39, s39, 0
	global_load_dwordx4 v[84:87], v6, s[38:39] nt
	global_load_dwordx4 v[88:91], v5, s[8:9]
	global_load_dwordx4 v[92:95], v5, s[8:9] offset:16
	s_cmp_eq_u32 s20, 0
	s_cbranch_scc1 .Ldf_exit
	s_waitcnt vmcnt(14)
	ds_write_b32 v3, v116 offset:0
	ds_write_b32 v3, v117 offset:4
	ds_write_b32 v3, v118 offset:8
	ds_write_b32 v3, v119 offset:12
	ds_write_b32 v3, v120 offset:1056
	ds_write_b32 v3, v121 offset:1060
	ds_write_b32 v3, v122 offset:1064
	ds_write_b32 v3, v123 offset:1068
	ds_write_b32 v3, v124 offset:2112
	ds_write_b32 v3, v125 offset:2116
	ds_write_b32 v3, v126 offset:2120
	ds_write_b32 v3, v127 offset:2124
	ds_write_b32 v3, v128 offset:3168
	ds_write_b32 v3, v129 offset:3172
	ds_write_b32 v3, v130 offset:3176
	ds_write_b32 v3, v131 offset:3180
	ds_write_b32 v3, v132 offset:4224
	ds_write_b32 v3, v133 offset:4228
	ds_write_b32 v3, v134 offset:4232
	ds_write_b32 v3, v135 offset:4236
	ds_write_b32 v3, v136 offset:5280
	ds_write_b32 v3, v137 offset:5284
	ds_write_b32 v3, v138 offset:5288
	ds_write_b32 v3, v139 offset:5292
	ds_write_b32 v3, v140 offset:6336
	ds_write_b32 v3, v141 offset:6340
	ds_write_b32 v3, v142 offset:6344
	ds_write_b32 v3, v143 offset:6348
	ds_write_b32 v3, v144 offset:7392
	ds_write_b32 v3, v145 offset:7396
	ds_write_b32 v3, v146 offset:7400
	ds_write_b32 v3, v147 offset:7404
	v_lshlrev_b32_e32 v7, 4, v1
	v_mad_u32_u24 v7, v2, s16, v7
	s_lshl_b32 s21, s16, 3
	s_waitcnt lgkmcnt(0)
	ds_read2_b32 v[16:17], v4 offset0:0 offset1:33
	ds_read2_b32 v[18:19], v4 offset0:66 offset1:99
	ds_read2_b32 v[20:21], v4 offset0:132 offset1:165
	ds_read2_b32 v[22:23], v4 offset0:198 offset1:231
	ds_read2_b32 v[24:25], v4 offset0:8 offset1:41
	ds_read2_b32 v[26:27], v4 offset0:74 offset1:107
	ds_read2_b32 v[28:29], v4 offset0:140 offset1:173
	ds_read2_b32 v[30:31], v4 offset0:206 offset1:239
	ds_read2_b32 v[32:33], v4 offset0:16 offset1:49
	ds_read2_b32 v[34:35], v4 offset0:82 offset1:115
	ds_read2_b32 v[36:37], v4 offset0:148 offset1:181
	ds_read2_b32 v[38:39], v4 offset0:214 offset1:247
	ds_read2_b32 v[40:41], v4 offset0:24 offset1:57
	ds_read2_b32 v[42:43], v4 offset0:90 offset1:123
	ds_read2_b32 v[44:45], v4 offset0:156 offset1:189
	ds_read2_b32 v[46:47], v4 offset0:222 offset1:255
	s_cmp_eq_u32 s17, 0
	s_waitcnt lgkmcnt(0)
	s_cbranch_scc1 .Ldf_nog_12
	v_mul_f32_e32 v16, v16, v148
	v_mul_f32_e32 v17, v17, v149
	v_mul_f32_e32 v18, v18, v150
	v_mul_f32_e32 v19, v19, v151
	v_mul_f32_e32 v20, v20, v152
	v_mul_f32_e32 v21, v21, v153
	v_mul_f32_e32 v22, v22, v154
	v_mul_f32_e32 v23, v23, v155
	v_mul_f32_e32 v24, v24, v148
	v_mul_f32_e32 v25, v25, v149
	v_mul_f32_e32 v26, v26, v150
	v_mul_f32_e32 v27, v27, v151
	v_mul_f32_e32 v28, v28, v152
	v_mul_f32_e32 v29, v29, v153
	v_mul_f32_e32 v30, v30, v154
	v_mul_f32_e32 v31, v31, v155
	v_mul_f32_e32 v32, v32, v148
	v_mul_f32_e32 v33, v33, v149
	v_mul_f32_e32 v34, v34, v150
	v_mul_f32_e32 v35, v35, v151
	v_mul_f32_e32 v36, v36, v152
	v_mul_f32_e32 v37, v37, v153
	v_mul_f32_e32 v38, v38, v154
	v_mul_f32_e32 v39, v39, v155
	v_mul_f32_e32 v40, v40, v148
	v_mul_f32_e32 v41, v41, v149
	v_mul_f32_e32 v42, v42, v150
	v_mul_f32_e32 v43, v43, v151
	v_mul_f32_e32 v44, v44, v152
	v_mul_f32_e32 v45, v45, v153
	v_mul_f32_e32 v46, v46, v154
	v_mul_f32_e32 v47, v47, v155
.Ldf_nog_12:
	v_cvt_pk_bf16_f32 v156, v16, v17
	v_cvt_pk_bf16_f32 v157, v18, v19
	v_cvt_pk_bf16_f32 v158, v20, v21
	v_cvt_pk_bf16_f32 v159, v22, v23
	v_cvt_pk_bf16_f32 v160, v24, v25
	v_cvt_pk_bf16_f32 v161, v26, v27
	v_cvt_pk_bf16_f32 v162, v28, v29
	v_cvt_pk_bf16_f32 v163, v30, v31
	v_cvt_pk_bf16_f32 v164, v32, v33
	v_cvt_pk_bf16_f32 v165, v34, v35
	v_cvt_pk_bf16_f32 v166, v36, v37
	v_cvt_pk_bf16_f32 v167, v38, v39
	v_cvt_pk_bf16_f32 v168, v40, v41
	v_cvt_pk_bf16_f32 v169, v42, v43
	v_cvt_pk_bf16_f32 v170, v44, v45
	v_cvt_pk_bf16_f32 v171, v46, v47
	global_store_dwordx4 v7, v[156:159], s[14:15]
	s_add_u32 s14, s14, s21
	s_addc_u32 s15, s15, 0
	global_store_dwordx4 v7, v[160:163], s[14:15]
	s_add_u32 s14, s14, s21
	s_addc_u32 s15, s15, 0
	global_store_dwordx4 v7, v[164:167], s[14:15]
	s_add_u32 s14, s14, s21
	s_addc_u32 s15, s15, 0
	global_store_dwordx4 v7, v[168:171], s[14:15]
	s_add_u32 s3, s3, s41
	s_cmp_lt_u32 s3, s49
	s_cselect_b32 s20, 1, 0
	s_cselect_b32 s21, s3, 0
	s_cmp_lt_u32 s21, 2816
	s_cbranch_scc1 .Ldf_k0_13
	s_sub_u32 s21, s21, 2816
	s_branch .Ldf_k1_14

.Ldf_go_15:
	v_lshlrev_b32_e32 v6, 4, v2
	v_mad_u32_u24 v6, v1, s27, v6
	s_lshl_b32 s27, s27, 3
	global_load_dwordx4 v[116:119], v6, s[38:39] nt
	s_add_u32 s38, s38, s27
	s_addc_u32 s39, s39, 0
	global_load_dwordx4 v[120:123], v6, s[38:39] nt
	s_add_u32 s38, s38, s27
	s_addc_u32 s39, s39, 0
	global_load_dwordx4 v[124:127], v6, s[38:39] nt
	s_add_u32 s38, s38, s27
	s_addc_u32 s39, s39, 0
	global_load_dwordx4 v[128:131], v6, s[38:39] nt
	s_add_u32 s38, s38, s27
	s_addc_u32 s39, s39, 0
	global_load_dwordx4 v[132:135], v6, s[38:39] nt
	s_add_u32 s38, s38, s27
	s_addc_u32 s39, s39, 0
	global_load_dwordx4 v[136:139], v6, s[38:39] nt
	s_add_u32 s38, s38, s27
	s_addc_u32 s39, s39, 0
	global_load_dwordx4 v[140:143], v6, s[38:39] nt
	s_add_u32 s38, s38, s27
	s_addc_u32 s39, s39, 0
	global_load_dwordx4 v[144:147], v6, s[38:39] nt
	global_load_dwordx4 v[148:151], v5, s[18:19]
	global_load_dwordx4 v[152:155], v5, s[18:19] offset:16
	s_cmp_eq_u32 s10, 0
	s_cbranch_scc1 .Ldf_exit
	s_waitcnt vmcnt(14)
	ds_write_b32 v3, v56 offset:0
	ds_write_b32 v3, v57 offset:4
	ds_write_b32 v3, v58 offset:8
	ds_write_b32 v3, v59 offset:12
	ds_write_b32 v3, v60 offset:1056
	ds_write_b32 v3, v61 offset:1060
	ds_write_b32 v3, v62 offset:1064
	ds_write_b32 v3, v63 offset:1068
	ds_write_b32 v3, v64 offset:2112
	ds_write_b32 v3, v65 offset:2116
	ds_write_b32 v3, v66 offset:2120
	ds_write_b32 v3, v67 offset:2124
	ds_write_b32 v3, v68 offset:3168
	ds_write_b32 v3, v69 offset:3172
	ds_write_b32 v3, v70 offset:3176
	ds_write_b32 v3, v71 offset:3180
	ds_write_b32 v3, v72 offset:4224
	ds_write_b32 v3, v73 offset:4228
	ds_write_b32 v3, v74 offset:4232
	ds_write_b32 v3, v75 offset:4236
	ds_write_b32 v3, v76 offset:5280
	ds_write_b32 v3, v77 offset:5284
	ds_write_b32 v3, v78 offset:5288
	ds_write_b32 v3, v79 offset:5292
	ds_write_b32 v3, v80 offset:6336
	ds_write_b32 v3, v81 offset:6340
	ds_write_b32 v3, v82 offset:6344
	ds_write_b32 v3, v83 offset:6348
	ds_write_b32 v3, v84 offset:7392
	ds_write_b32 v3, v85 offset:7396
	ds_write_b32 v3, v86 offset:7400
	ds_write_b32 v3, v87 offset:7404
	v_lshlrev_b32_e32 v7, 4, v1
	v_mad_u32_u24 v7, v2, s6, v7
	s_lshl_b32 s21, s6, 3
	s_waitcnt lgkmcnt(0)
	ds_read2_b32 v[16:17], v4 offset0:0 offset1:33
	ds_read2_b32 v[18:19], v4 offset0:66 offset1:99
	ds_read2_b32 v[20:21], v4 offset0:132 offset1:165
	ds_read2_b32 v[22:23], v4 offset0:198 offset1:231
	ds_read2_b32 v[24:25], v4 offset0:8 offset1:41
	ds_read2_b32 v[26:27], v4 offset0:74 offset1:107
	ds_read2_b32 v[28:29], v4 offset0:140 offset1:173
	ds_read2_b32 v[30:31], v4 offset0:206 offset1:239
	ds_read2_b32 v[32:33], v4 offset0:16 offset1:49
	ds_read2_b32 v[34:35], v4 offset0:82 offset1:115
	ds_read2_b32 v[36:37], v4 offset0:148 offset1:181
	ds_read2_b32 v[38:39], v4 offset0:214 offset1:247
	ds_read2_b32 v[40:41], v4 offset0:24 offset1:57
	ds_read2_b32 v[42:43], v4 offset0:90 offset1:123
	ds_read2_b32 v[44:45], v4 offset0:156 offset1:189
	ds_read2_b32 v[46:47], v4 offset0:222 offset1:255
	s_cmp_eq_u32 s7, 0
	s_waitcnt lgkmcnt(0)
	s_cbranch_scc1 .Ldf_nog_16
	v_mul_f32_e32 v16, v16, v88
	v_mul_f32_e32 v17, v17, v89
	v_mul_f32_e32 v18, v18, v90
	v_mul_f32_e32 v19, v19, v91
	v_mul_f32_e32 v20, v20, v92
	v_mul_f32_e32 v21, v21, v93
	v_mul_f32_e32 v22, v22, v94
	v_mul_f32_e32 v23, v23, v95
	v_mul_f32_e32 v24, v24, v88
	v_mul_f32_e32 v25, v25, v89
	v_mul_f32_e32 v26, v26, v90
	v_mul_f32_e32 v27, v27, v91
	v_mul_f32_e32 v28, v28, v92
	v_mul_f32_e32 v29, v29, v93
	v_mul_f32_e32 v30, v30, v94
	v_mul_f32_e32 v31, v31, v95
	v_mul_f32_e32 v32, v32, v88
	v_mul_f32_e32 v33, v33, v89
	v_mul_f32_e32 v34, v34, v90
	v_mul_f32_e32 v35, v35, v91
	v_mul_f32_e32 v36, v36, v92
	v_mul_f32_e32 v37, v37, v93
	v_mul_f32_e32 v38, v38, v94
	v_mul_f32_e32 v39, v39, v95
	v_mul_f32_e32 v40, v40, v88
	v_mul_f32_e32 v41, v41, v89
	v_mul_f32_e32 v42, v42, v90
	v_mul_f32_e32 v43, v43, v91
	v_mul_f32_e32 v44, v44, v92
	v_mul_f32_e32 v45, v45, v93
	v_mul_f32_e32 v46, v46, v94
	v_mul_f32_e32 v47, v47, v95
.Ldf_nog_16:
	v_cvt_pk_bf16_f32 v156, v16, v17
	v_cvt_pk_bf16_f32 v157, v18, v19
	v_cvt_pk_bf16_f32 v158, v20, v21
	v_cvt_pk_bf16_f32 v159, v22, v23
	v_cvt_pk_bf16_f32 v160, v24, v25
	v_cvt_pk_bf16_f32 v161, v26, v27
	v_cvt_pk_bf16_f32 v162, v28, v29
	v_cvt_pk_bf16_f32 v163, v30, v31
	v_cvt_pk_bf16_f32 v164, v32, v33
	v_cvt_pk_bf16_f32 v165, v34, v35
	v_cvt_pk_bf16_f32 v166, v36, v37
	v_cvt_pk_bf16_f32 v167, v38, v39
	v_cvt_pk_bf16_f32 v168, v40, v41
	v_cvt_pk_bf16_f32 v169, v42, v43
	v_cvt_pk_bf16_f32 v170, v44, v45
	v_cvt_pk_bf16_f32 v171, v46, v47
	global_store_dwordx4 v7, v[156:159], s[4:5]
	s_add_u32 s4, s4, s21
	s_addc_u32 s5, s5, 0
	global_store_dwordx4 v7, v[160:163], s[4:5]
	s_add_u32 s4, s4, s21
	s_addc_u32 s5, s5, 0
	global_store_dwordx4 v7, v[164:167], s[4:5]
	s_add_u32 s4, s4, s21
	s_addc_u32 s5, s5, 0
	global_store_dwordx4 v7, v[168:171], s[4:5]
	s_branch .Ldf_loop
.Ldf_exit:
	s_waitcnt vmcnt(0)
	s_waitcnt lgkmcnt(0)
	v_readlane_b32 s60, v254, 24
	v_readlane_b32 s62, v254, 27
	v_readlane_b32 s46, v254, 29
	v_readlane_b32 s48, v254, 31
	v_readlane_b32 s50, v254, 33
	v_readlane_b32 s52, v254, 35
	v_readlane_b32 s54, v254, 37
	v_readlane_b32 s56, v254, 39
	v_readlane_b32 s64, v254, 41
	v_readlane_b32 s68, v254, 43
	v_readlane_b32 s70, v254, 45
	v_readlane_b32 s72, v254, 47
	v_readlane_b32 s74, v254, 49
	v_readlane_b32 s84, v254, 52
	v_readlane_b32 s88, v254, 54
	v_readlane_b32 s96, v255, 7
	v_readlane_b32 s61, v254, 25
	v_readlane_b32 s59, v254, 26
	v_readlane_b32 s63, v254, 28
	v_readlane_b32 s47, v254, 30
	v_readlane_b32 s49, v254, 32
	v_readlane_b32 s51, v254, 34
	v_readlane_b32 s53, v254, 36
	v_readlane_b32 s55, v254, 38
	v_readlane_b32 s57, v254, 40
	v_readlane_b32 s65, v254, 42
	v_readlane_b32 s69, v254, 44
	v_readlane_b32 s71, v254, 46
	v_readlane_b32 s73, v254, 48
	v_readlane_b32 s75, v254, 50
	s_mov_b32 s58, 0xbfb8aa3b
	s_mov_b32 s77, 0x800000
	s_movk_i32 s67, 0x4000
	s_mov_b32 s78, 0x8000
	s_mov_b32 s79, 0xc000
	s_mov_b32 s80, 0xfffff
	s_mov_b32 s81, 0x3f317217
	s_mov_b32 s82, 0x7f800000
	v_readlane_b32 s85, v254, 53
	v_readlane_b32 s86, v255, 0
	v_readlane_b32 s89, v254, 55
	v_readlane_b32 s90, v254, 56
	v_readlane_b32 s91, v254, 57
	v_readlane_b32 s92, v254, 58
	v_readlane_b32 s93, v254, 59
	v_readlane_b32 s94, v254, 60
	v_readlane_b32 s95, v254, 61
	v_readlane_b32 s97, v255, 8
	v_readlane_b32 s98, v255, 9
	v_readlane_b32 s99, v255, 10
	v_readlane_b32 s42, v255, 11
	v_readlane_b32 s87, v255, 1
	v_readlane_b32 s43, v255, 12
